# v14_xcd
# speedup vs baseline: 1.0522x; 1.0112x over previous
; #define ACC_LOOP _Pragma("unroll") for (int ai = 0; ai < 2; ++ai) _Pragma("unroll") for (int bj = 0; bj < 2; ++bj) \
;                  _Pragma("unroll") for (int m = 0; m < 4; ++m) _Pragma("unroll") for (int n = 0; n < 2; ++n)
; __device__ void phase1(const Params& p) {
;     ...
;       ACC_LOOP {
;         u32x2 o;
;         o[0] = pack2(acc[ai][bj][m][n][0], acc[ai][bj][m][n][1]);
;         o[1] = pack2(acc[ai][bj][m][n][2], acc[ai][bj][m][n][3]);
;         *(u32x2*)(p.PROJ + (size_t)ACC_ROW * NP + ACC_COL) = o;
;       }
.LBB0_75:
	s_cmp_gt_i32 s89, 63
	s_cbranch_scc1 .LBB0_77
	v_ashrrev_i32_e32 v137, 31, v136
	v_lshlrev_b64 v[130:131], 15, v[136:137]
	v_lshl_add_u64 v[130:131], s[74:75], 0, v[130:131]
	v_ashrrev_i32_e32 v129, 31, v128
	v_lshl_add_u64 v[128:129], v[128:129], 1, v[130:131]
	v_and_b32_e32 v130, 16, v248
	v_lshrrev_b32_e32 v131, 1, v130
	v_add_u32_e32 v130, v130, v131
	v_mov_b32_e32 v131, 0
	v_lshl_add_u64 v[128:129], v[128:129], 0, v[130:131]
	v_cvt_pk_bf16_f32 v140, v16, v17
	v_cvt_pk_bf16_f32 v141, v18, v19
	v_cvt_pk_bf16_f32 v142, v20, v21
	v_cvt_pk_bf16_f32 v143, v22, v23
	s_nop 1
	v_permlane16_swap_b32_e32 v140, v142
	v_permlane16_swap_b32_e32 v141, v143
	global_store_dwordx4 v[128:129], v[140:143], off
	v_cvt_pk_bf16_f32 v136, v124, v125
	v_cvt_pk_bf16_f32 v137, v126, v127
	v_cvt_pk_bf16_f32 v138, v120, v121
	v_cvt_pk_bf16_f32 v139, v122, v123
	s_nop 1
	v_permlane16_swap_b32_e32 v136, v138
	v_permlane16_swap_b32_e32 v137, v139
	global_store_dwordx4 v[128:129], v[136:139], off offset:256
	s_mov_b64 s[0:1], 0x80000
	v_lshl_add_u64 v[130:131], v[128:129], 0, s[0:1]
	v_cvt_pk_bf16_f32 v140, v24, v25
	v_cvt_pk_bf16_f32 v141, v26, v27
	v_cvt_pk_bf16_f32 v142, v28, v29
	v_cvt_pk_bf16_f32 v143, v30, v31
	s_nop 1
	v_permlane16_swap_b32_e32 v140, v142
	v_permlane16_swap_b32_e32 v141, v143
	global_store_dwordx4 v[130:131], v[140:143], off
	v_cvt_pk_bf16_f32 v136, v116, v117
	v_cvt_pk_bf16_f32 v137, v118, v119
	v_cvt_pk_bf16_f32 v138, v112, v113
	v_cvt_pk_bf16_f32 v139, v114, v115
	s_nop 1
	v_permlane16_swap_b32_e32 v136, v138
	v_permlane16_swap_b32_e32 v137, v139
	global_store_dwordx4 v[130:131], v[136:139], off offset:256
	s_mov_b64 s[0:1], 0x100000
	v_lshl_add_u64 v[130:131], v[128:129], 0, s[0:1]
	v_cvt_pk_bf16_f32 v140, v0, v1
	v_cvt_pk_bf16_f32 v141, v2, v3
	v_cvt_pk_bf16_f32 v142, v8, v9
	v_cvt_pk_bf16_f32 v143, v10, v11
	s_nop 1
	v_permlane16_swap_b32_e32 v140, v142
	v_permlane16_swap_b32_e32 v141, v143
	global_store_dwordx4 v[130:131], v[140:143], off
	v_cvt_pk_bf16_f32 v136, v108, v109
	v_cvt_pk_bf16_f32 v137, v110, v111
	v_cvt_pk_bf16_f32 v138, v104, v105
	v_cvt_pk_bf16_f32 v139, v106, v107
	s_nop 1
	v_permlane16_swap_b32_e32 v136, v138
	v_permlane16_swap_b32_e32 v137, v139
	global_store_dwordx4 v[130:131], v[136:139], off offset:256
	s_mov_b64 s[0:1], 0x180000
	v_lshl_add_u64 v[130:131], v[128:129], 0, s[0:1]
	v_cvt_pk_bf16_f32 v140, v4, v5
	v_cvt_pk_bf16_f32 v141, v6, v7
	v_cvt_pk_bf16_f32 v142, v12, v13
	v_cvt_pk_bf16_f32 v143, v14, v15
	s_nop 1
	v_permlane16_swap_b32_e32 v140, v142
	v_permlane16_swap_b32_e32 v141, v143
	global_store_dwordx4 v[130:131], v[140:143], off
	v_cvt_pk_bf16_f32 v136, v100, v101
	v_cvt_pk_bf16_f32 v137, v102, v103
	v_cvt_pk_bf16_f32 v138, v96, v97
	v_cvt_pk_bf16_f32 v139, v98, v99
	s_nop 1
	v_permlane16_swap_b32_e32 v136, v138
	v_permlane16_swap_b32_e32 v137, v139
	global_store_dwordx4 v[130:131], v[136:139], off offset:256
	s_mov_b64 s[0:1], 0x400000
	v_lshl_add_u64 v[130:131], v[128:129], 0, s[0:1]
	v_cvt_pk_bf16_f32 v140, v48, v49
	v_cvt_pk_bf16_f32 v141, v50, v51
	v_cvt_pk_bf16_f32 v142, v56, v57
	v_cvt_pk_bf16_f32 v143, v58, v59
	s_nop 1
	v_permlane16_swap_b32_e32 v140, v142
	v_permlane16_swap_b32_e32 v141, v143
	global_store_dwordx4 v[130:131], v[140:143], off
	v_cvt_pk_bf16_f32 v136, v92, v93
	v_cvt_pk_bf16_f32 v137, v94, v95
	v_cvt_pk_bf16_f32 v138, v88, v89
	v_cvt_pk_bf16_f32 v139, v90, v91
	s_nop 1
	v_permlane16_swap_b32_e32 v136, v138
	v_permlane16_swap_b32_e32 v137, v139
	global_store_dwordx4 v[130:131], v[136:139], off offset:256
	s_mov_b64 s[0:1], 0x480000
	v_lshl_add_u64 v[130:131], v[128:129], 0, s[0:1]
	v_cvt_pk_bf16_f32 v140, v52, v53
	v_cvt_pk_bf16_f32 v141, v54, v55
	v_cvt_pk_bf16_f32 v142, v60, v61
	v_cvt_pk_bf16_f32 v143, v62, v63
	s_nop 1
	v_permlane16_swap_b32_e32 v140, v142
	v_permlane16_swap_b32_e32 v141, v143
	global_store_dwordx4 v[130:131], v[140:143], off
	v_cvt_pk_bf16_f32 v136, v84, v85
	v_cvt_pk_bf16_f32 v137, v86, v87
	v_cvt_pk_bf16_f32 v138, v80, v81
	v_cvt_pk_bf16_f32 v139, v82, v83
	s_nop 1
	v_permlane16_swap_b32_e32 v136, v138
	v_permlane16_swap_b32_e32 v137, v139
	global_store_dwordx4 v[130:131], v[136:139], off offset:256
	s_mov_b64 s[0:1], 0x500000
	v_lshl_add_u64 v[130:131], v[128:129], 0, s[0:1]
	v_cvt_pk_bf16_f32 v140, v32, v33
	v_cvt_pk_bf16_f32 v141, v34, v35
	v_cvt_pk_bf16_f32 v142, v40, v41
	v_cvt_pk_bf16_f32 v143, v42, v43
	s_nop 1
	v_permlane16_swap_b32_e32 v140, v142
	v_permlane16_swap_b32_e32 v141, v143
	global_store_dwordx4 v[130:131], v[140:143], off
	v_cvt_pk_bf16_f32 v136, v76, v77
	v_cvt_pk_bf16_f32 v137, v78, v79
	v_cvt_pk_bf16_f32 v138, v72, v73
	v_cvt_pk_bf16_f32 v139, v74, v75
	s_nop 1
	v_permlane16_swap_b32_e32 v136, v138
	v_permlane16_swap_b32_e32 v137, v139
	global_store_dwordx4 v[130:131], v[136:139], off offset:256
	s_mov_b64 s[0:1], 0x580000
	v_lshl_add_u64 v[130:131], v[128:129], 0, s[0:1]
	v_cvt_pk_bf16_f32 v140, v36, v37
	v_cvt_pk_bf16_f32 v141, v38, v39
	v_cvt_pk_bf16_f32 v142, v44, v45
	v_cvt_pk_bf16_f32 v143, v46, v47
	s_nop 1
	v_permlane16_swap_b32_e32 v140, v142
	v_permlane16_swap_b32_e32 v141, v143
	global_store_dwordx4 v[130:131], v[140:143], off
	v_cvt_pk_bf16_f32 v136, v68, v69
	v_cvt_pk_bf16_f32 v137, v70, v71
	v_cvt_pk_bf16_f32 v138, v64, v65
	v_cvt_pk_bf16_f32 v139, v66, v67
	s_nop 1
	v_permlane16_swap_b32_e32 v136, v138
	v_permlane16_swap_b32_e32 v137, v139
	global_store_dwordx4 v[130:131], v[136:139], off offset:256
	s_mov_b64 s[0:1], 0

; __device__ void phase2(const Params& p, const int rep) {
;     ...
;   for (;;) {
;     if (threadIdx.x == 0) *sid = atomicAdd(p.counters + rep, 1);
;     __syncthreads();
;     int id = *sid;
;     __syncthreads();
;     if (id >= 3072) break;
;     attn_item(p, 3071 - id);
.LBB0_448:
	s_getreg_b32 s98, hwreg(HW_REG_XCC_ID, 0, 4)
	s_mov_b32 s100, 0
	s_and_b32 s98, s98, 7
	v_mbcnt_hi_u32_b32 v249, -1, v160
	v_and_b32_e32 v0, 64, v249
	s_mov_b32 s9, 0
	v_mov_b32_e32 v65, 0
	v_mov_b32_e32 v68, 0x222e0
	s_movk_i32 s2, 0xbff
	s_movk_i32 s3, 0x800
	s_movk_i32 s11, 0x880
	s_mov_b32 s15, 0xffff0000
	s_mov_b32 s16, 0x11000
	s_movk_i32 s17, 0x110
	s_mov_b32 s18, 0x42fc0000
	s_mov_b32 s14, 0x3db504f3
	s_mov_b32 s19, 0xf149f2ca
	s_mov_b32 s28, 0xefa18f08
	s_movk_i32 s29, 0x41
	s_movk_i32 s30, 0xffbe
	s_movk_i32 s31, 0x210
	s_mov_b32 s34, 0x800000
	s_mov_b32 s35, 0x3f317217
	s_mov_b32 s46, 0x7f800000
	v_mov_b32_e32 v69, 0x42800000
	v_xor_b32_e32 v189, 16, v249
	v_add_u32_e32 v250, 64, v0
	v_xor_b32_e32 v251, 32, v249
	v_mov_b32_e32 v70, 0xf149f2ca
	v_mov_b32_e32 v71, 0x11000
	v_mov_b32_e32 v72, 0x13100
	v_mov_b32_e32 v73, 0x15200
	v_mov_b32_e32 v74, 0x17300
	v_mov_b32_e32 v75, 0x1b500
	v_mov_b32_e32 v76, 0x1d600
	v_mov_b32_e32 v77, 0x1f700
	v_mov_b32_e32 v78, 0x41b17218
	s_branch .LBB0_451

; __device__ void phase2(const Params& p, const int rep) {
;     ...
;     if (threadIdx.x == 0) *sid = atomicAdd(p.counters + rep, 1);
.LBB0_451:
	s_and_saveexec_b64 s[0:1], s[72:73]
	s_cbranch_execz .LBB0_455
	s_mov_b64 s[6:7], exec
	v_mbcnt_lo_u32_b32 v0, s6, 0
	v_mbcnt_hi_u32_b32 v0, s7, v0
	v_cmp_eq_u32_e32 vcc, 0, v0
	s_and_saveexec_b64 s[4:5], vcc
	s_cbranch_execz .LBB0_454
	s_bcnt1_i32_b64 s6, s[6:7]
	v_mov_b32_e32 v1, s6
	s_lshl_b32 s101, s98, 2
	s_add_i32 s101, s101, 32
	v_mov_b32_e32 v2, s101
	global_atomic_add v1, v2, v1, s[48:49] sc0

; __device__ void attn_item(const Params& p, int id) {
;     ...
;   const int tid = tid_, lane = tid & 63, w = tid >> 6, fr = lane & 15, fq = lane >> 4;
;   const int g = id >> 10, rem = id & 1023, h = rem & 7, tb = rem >> 3;
;   int seq, local;
;   if (tb < 64) { seq = tb >> 4; local = tb & 15; } else { seq = 4; local = tb - 64; }
;   const int dsh = g * 2, d = 1 << dsh;
;   const int start = seq_start(seq), len = seq_len(seq), L = len >> dsh, nub = L >> 7;
;   const int r = local / nub, ub = local % nub, u0 = ub * 128;
;   u16* KL = (u16*)smem;
;   u16* VT = (u16*)(smem + 69632);
;   const u16* base = p.PROJ + C_QKV + g * 3072 + h * 128;
;   {
;     const int c8 = tid & 15, kb = tid >> 4;
;     u32x4 kr[8], vr[8], vo[8];
; #pragma unroll
;     for (int k = 0; k < 8; ++k) {
;       int j = 8 * kb + k;
;       int u = u0 - 64 + j;
;       bool valid = (u >= 0) && (u < L);
;       u32x4 z = {0u, 0u, 0u, 0u};
;       kr[k] = z; vr[k] = z;
;       if (valid) {
;         const u16* src = base + (size_t)(start + r + d * u) * NP + c8 * 8;
;         kr[k] = *(const u32x4*)(src + 1024);
;         vr[k] = *(const u32x4*)(src + 2048);
;       }
; __device__ void phase2(const Params& p, const int rep) {
;     ...
;     if (threadIdx.x == 0) *sid = atomicAdd(p.counters + rep, 1);
;     __syncthreads();
;     int id = *sid;
;     __syncthreads();
;     if (id >= 3072) break;
;     attn_item(p, 3071 - id);
.LBB0_455:
	s_or_b64 exec, exec, s[0:1]
	s_waitcnt lgkmcnt(0)
	s_barrier
	ds_read_b32 v0, v68
	s_waitcnt lgkmcnt(0)
	s_barrier
	v_readfirstlane_b32 s4, v0
	s_cmpk_lt_u32 s4, 0x180
	s_cbranch_scc1 .Lat_have
	s_add_i32 s98, s98, 1
	s_add_i32 s100, s100, 1
	s_and_b32 s98, s98, 7
	s_cmp_ge_u32 s100, 8
	s_cselect_b64 s[0:1], -1, 0
	s_branch .LBB0_450
.Lat_have:
	s_lshr_b32 s5, s4, 6
	s_and_b32 s4, s4, 63
	s_lshl_b32 s5, s5, 9
	s_or_b32 s4, s4, s5
	s_lshl_b32 s5, s98, 6
	s_or_b32 s4, s4, s5
	s_sub_i32 s4, 0xbff, s4
	s_bfe_u32 s6, s4, 0x70003
	s_lshr_b32 s8, s4, 10
	s_and_b32 s47, s4, 7
	v_sub_co_u32_e64 v0, s[0:1], s6, 64
	s_bfe_u32 s7, s4, 0x40003
	s_and_b64 s[4:5], s[0:1], exec
	v_readfirstlane_b32 s4, v0
	s_cselect_b32 s7, s7, s4
	s_min_u32 s4, s6, 64
	s_lshl_b32 s4, s4, 7
	s_lshl_b32 s6, s8, 1
	s_and_b32 s56, s4, 0x3800
	s_and_b64 s[4:5], s[0:1], exec
	s_cselect_b32 s4, s3, 0x2000
	s_lshr_b32 s57, s4, s6
	s_lshr_b32 s4, s57, 7
	s_and_b64 s[0:1], s[0:1], exec
	s_cselect_b32 s0, 11, 13
	s_sub_i32 s0, s0, s6
	s_add_i32 s0, s0, 0xfff9
	s_and_b32 s1, s7, 0xff
	s_add_i32 s4, s4, -1
	s_lshr_b32 s5, s1, s0
	s_and_b32 s0, s4, s7
	s_lshl_b32 s0, s0, 7
	s_and_b32 s7, s0, 0x7f80
	s_mul_i32 s0, s8, 0xc00
	s_mov_b32 s1, s9
	s_lshl_b64 s[0:1], s[0:1], 1
	s_add_u32 s0, s74, s0
	s_addc_u32 s1, s75, s1
	s_lshl_b32 s4, s47, 8
	v_mov_b32_e32 v79, v248
	s_add_u32 s0, s0, s4
	s_addc_u32 s1, s1, 0
	v_and_b32_e32 v80, 15, v79
	v_ashrrev_i32_e32 v81, 4, v79
	s_sub_i32 s4, s7, 64
	v_lshl_add_u32 v37, v81, 3, s4
	v_lshlrev_b32_e32 v64, 4, v80
	s_or_b32 s58, s56, s5
	v_lshl_add_u64 v[66:67], s[0:1], 0, v[64:65]
	v_cmp_gt_u32_e32 vcc, s57, v37
	v_mov_b32_e32 v0, 0
	v_mov_b32_e32 v4, 0
	v_mov_b32_e32 v5, 0
	v_mov_b32_e32 v6, 0
	v_mov_b32_e32 v7, 0
	v_mov_b32_e32 v16, 0
	v_mov_b32_e32 v17, 0
	v_mov_b32_e32 v18, 0
	v_mov_b32_e32 v19, 0
	s_and_saveexec_b64 s[4:5], vcc
	s_cbranch_execz .LBB0_458
	v_lshlrev_b32_e32 v1, s6, v37
	v_add_u32_e32 v2, s58, v1
	v_ashrrev_i32_e32 v3, 31, v2
	v_lshlrev_b64 v[2:3], 15, v[2:3]
	v_lshl_add_u64 v[2:3], v[66:67], 0, v[2:3]
	v_add_co_u32_e32 v4, vcc, 0x1000, v2
	s_nop 1
	v_addc_co_u32_e32 v5, vcc, 0, v3, vcc
	global_load_dwordx4 v[16:19], v[2:3], off offset:2048
	s_nop 0
	global_load_dwordx4 v[4:7], v[4:5], off

; __device__ void phase4(const Params& p) {
;     ...
;     for (int ai = 0; ai < 2; ++ai)
; #pragma unroll
;       for (int m = 0; m < 4; ++m) {
;         const int row = ACC_ROW;
;         const float* x = row < 8192 ? p.x_prompt + (size_t)row * DM : p.x_sample + (size_t)(row - 8192) * DM;
;         float ss = 0.f;
; #pragma unroll
;         for (int bj = 0; bj < 2; ++bj)
; #pragma unroll
;           for (int n = 0; n < 2; ++n) {
;             const int col = ACC_COL;
;             f32x4 xv = *(const f32x4*)(x + col);
;             f32x4 v = xv + acc[ai][bj][m][n];
;             ss += v[0] * v[0] + v[1] * v[1] + v[2] * v[2] + v[3] * v[3];
;             acc[ai][bj][m][n] = v;
;             if (!fused) *(f32x4*)(p.out + (size_t)row * DM + col) = v;
;           }
;         ss += __shfl_xor(ss, 16);
;         ss += __shfl_xor(ss, 32);
;         if (fq == 0) {
;           if (fused) __hip_atomic_store(p.PART + (size_t)row * 64 + pn * 4 + wc, ss, __ATOMIC_RELAXED, __HIP_MEMORY_SCOPE_AGENT);
;           else p.PART[(size_t)row * 64 + pn * 4 + wc] = ss;
;         }
.LBB0_634:
	v_add_u32_e32 v154, s34, v145
	v_or_b32_e32 v128, s8, v184
	s_nop 0
	v_cmp_lt_i32_e32 vcc, s58, v154
	s_and_saveexec_b64 s[2:3], vcc
	s_xor_b64 s[2:3], exec, s[2:3]
	v_add_u32_e32 v146, 0xffffe000, v154
	v_lshlrev_b64 v[130:131], 14, v[146:147]
	v_mov_b32_e32 v155, v147
	v_lshl_add_u64 v[130:131], s[54:55], 0, v[130:131]
	v_lshlrev_b64 v[132:133], 14, v[154:155]
	s_andn2_saveexec_b64 s[2:3], s[2:3]
	v_ashrrev_i32_e32 v155, 31, v154
	v_lshlrev_b64 v[132:133], 14, v[154:155]
	v_lshl_add_u64 v[130:131], s[52:53], 0, v[132:133]
	s_or_b64 exec, exec, s[2:3]
	v_ashrrev_i32_e32 v129, 31, v128
	v_lshl_add_u64 v[130:131], v[128:129], 2, v[130:131]
	v_mov_b32_e32 v240, v130
	v_mov_b32_e32 v241, v131
	s_mov_b32 s101, 0
	global_load_dwordx4 v[192:195], v[240:241], off
	global_load_dwordx4 v[196:199], v[240:241], off offset:64
	global_load_dwordx4 v[200:203], v[240:241], off offset:512
	global_load_dwordx4 v[204:207], v[240:241], off offset:576
	s_mov_b32 s100, 0x40000
	v_lshl_add_u64 v[246:247], v[240:241], 0, s[100:101]
	global_load_dwordx4 v[208:211], v[246:247], off
	global_load_dwordx4 v[212:215], v[246:247], off offset:64
	global_load_dwordx4 v[216:219], v[246:247], off offset:512
	global_load_dwordx4 v[220:223], v[246:247], off offset:576
	s_mov_b32 s100, 0x80000
	v_lshl_add_u64 v[246:247], v[240:241], 0, s[100:101]
	global_load_dwordx4 v[224:227], v[246:247], off
	global_load_dwordx4 v[228:231], v[246:247], off offset:64
	global_load_dwordx4 v[232:235], v[246:247], off offset:512
	global_load_dwordx4 v[236:239], v[246:247], off offset:576
	v_cndmask_b32_e64 v138, 0, 1, s[12:13]
	v_lshl_add_u64 v[150:151], s[22:23], 0, v[132:133]
	v_cmp_ne_u32_e64 s[8:9], 1, v138
	s_andn2_b64 vcc, exec, s[12:13]
	v_lshl_add_u64 v[132:133], v[128:129], 2, v[150:151]
	s_waitcnt vmcnt(8)
	v_pk_add_f32 v[2:3], v[2:3], v[194:195]
	v_pk_add_f32 v[0:1], v[0:1], v[192:193]
	s_cbranch_vccnz .LBB0_640
	global_store_dwordx4 v[132:133], v[0:3], off
.LBB0_640:
	s_and_b64 vcc, exec, s[8:9]
	v_pk_add_f32 v[6:7], v[6:7], v[198:199]
	v_pk_add_f32 v[4:5], v[4:5], v[196:197]
	s_cbranch_vccnz .LBB0_642
	global_store_dwordx4 v[132:133], v[4:7], off offset:64
.LBB0_642:
	s_and_b64 vcc, exec, s[8:9]
	v_pk_add_f32 v[10:11], v[10:11], v[202:203]
	v_pk_add_f32 v[8:9], v[8:9], v[200:201]
	s_cbranch_vccnz .LBB0_644
	global_store_dwordx4 v[132:133], v[8:11], off offset:512
.LBB0_644:
	s_and_b64 vcc, exec, s[8:9]
	v_pk_add_f32 v[14:15], v[14:15], v[206:207]
	v_pk_add_f32 v[12:13], v[12:13], v[204:205]
	s_cbranch_vccnz .LBB0_646
	global_store_dwordx4 v[132:133], v[12:15], off offset:576
.LBB0_646:
	s_mov_b32 s100, 0xc0000
	v_lshl_add_u64 v[246:247], v[240:241], 0, s[100:101]
	global_load_dwordx4 v[192:195], v[246:247], off
	global_load_dwordx4 v[196:199], v[246:247], off offset:64
	global_load_dwordx4 v[200:203], v[246:247], off offset:512
	global_load_dwordx4 v[204:207], v[246:247], off offset:576
	v_mul_f32_e32 v130, v1, v1
	v_mul_f32_e32 v131, v5, v5
	v_fmac_f32_e32 v130, v0, v0
	v_fmac_f32_e32 v131, v4, v4
	v_fmac_f32_e32 v130, v2, v2
	v_fmac_f32_e32 v131, v6, v6
	v_fmac_f32_e32 v130, v3, v3
	v_fmac_f32_e32 v131, v7, v7
	v_add_f32_e32 v130, v130, v131
	v_mul_f32_e32 v131, v9, v9
	v_fmac_f32_e32 v131, v8, v8
	v_fmac_f32_e32 v131, v10, v10
	v_fmac_f32_e32 v131, v11, v11
	v_add_f32_e32 v130, v130, v131
	v_mul_f32_e32 v131, v13, v13
	v_fmac_f32_e32 v131, v12, v12
	v_fmac_f32_e32 v131, v14, v14
	v_fmac_f32_e32 v131, v15, v15
	v_cmp_lt_i32_e32 vcc, v189, v250
	v_add_f32_e32 v130, v130, v131
	s_lshl_b32 s2, s37, 2
	v_cndmask_b32_e32 v131, v249, v189, vcc
	v_lshlrev_b32_e32 v134, 2, v131
	ds_bpermute_b32 v131, v134, v130
	v_cmp_lt_i32_e32 vcc, v251, v250
	s_ashr_i32 s3, s2, 31
	v_lshlrev_b32_e32 v146, 2, v144
	v_cndmask_b32_e32 v132, v249, v251, vcc
	v_lshlrev_b32_e32 v135, 2, v132
	s_waitcnt lgkmcnt(0)
	v_add_f32_e32 v130, v130, v131
	ds_bpermute_b32 v131, v135, v130
	s_and_saveexec_b64 s[40:41], s[0:1]
	s_cbranch_execz .LBB0_651
	s_waitcnt lgkmcnt(0)
	v_add_f32_e32 v132, v130, v131
	v_lshlrev_b64 v[130:131], 8, v[154:155]
	v_lshl_add_u64 v[130:131], s[44:45], 0, v[130:131]
	v_lshl_add_u64 v[130:131], s[2:3], 2, v[130:131]
	v_lshl_add_u64 v[130:131], v[130:131], 0, v[146:147]
	s_mov_b64 s[42:43], -1
	s_and_b64 vcc, exec, s[12:13]
	s_cbranch_vccz .LBB0_649
	global_store_dword v[130:131], v132, off
	s_mov_b64 s[42:43], 0

; __device__ void phase4(const Params& p) {
;     ...
;     for (int ai = 0; ai < 2; ++ai)
; #pragma unroll
;       for (int m = 0; m < 4; ++m) {
;         const int row = ACC_ROW;
;         const float* x = row < 8192 ? p.x_prompt + (size_t)row * DM : p.x_sample + (size_t)(row - 8192) * DM;
;         float ss = 0.f;
; #pragma unroll
;         for (int bj = 0; bj < 2; ++bj)
; #pragma unroll
;           for (int n = 0; n < 2; ++n) {
;             const int col = ACC_COL;
;             f32x4 xv = *(const f32x4*)(x + col);
;             f32x4 v = xv + acc[ai][bj][m][n];
;             ss += v[0] * v[0] + v[1] * v[1] + v[2] * v[2] + v[3] * v[3];
;             acc[ai][bj][m][n] = v;
;             if (!fused) *(f32x4*)(p.out + (size_t)row * DM + col) = v;
;           }
;         ss += __shfl_xor(ss, 16);
;         ss += __shfl_xor(ss, 32);
;         if (fq == 0) {
;           if (fused) __hip_atomic_store(p.PART + (size_t)row * 64 + pn * 4 + wc, ss, __ATOMIC_RELAXED, __HIP_MEMORY_SCOPE_AGENT);
;           else p.PART[(size_t)row * 64 + pn * 4 + wc] = ss;
;         }
.LBB0_655:
	s_or_b64 exec, exec, s[40:41]
	v_lshl_add_u64 v[132:133], v[128:129], 2, v[132:133]
	s_waitcnt lgkmcnt(0)
	v_lshl_add_u64 v[152:153], s[22:23], 0, v[130:131]
	s_and_b64 vcc, exec, s[8:9]
	v_lshl_add_u64 v[130:131], v[128:129], 2, v[152:153]
	s_waitcnt vmcnt(9)
	v_pk_add_f32 v[18:19], v[18:19], v[210:211]
	v_pk_add_f32 v[16:17], v[16:17], v[208:209]
	s_cbranch_vccnz .LBB0_657
	global_store_dwordx4 v[130:131], v[16:19], off
.LBB0_657:
	s_and_b64 vcc, exec, s[8:9]
	v_pk_add_f32 v[22:23], v[22:23], v[214:215]
	v_pk_add_f32 v[20:21], v[20:21], v[212:213]
	s_cbranch_vccnz .LBB0_659
	global_store_dwordx4 v[130:131], v[20:23], off offset:64
.LBB0_659:
	s_and_b64 vcc, exec, s[8:9]
	v_pk_add_f32 v[26:27], v[26:27], v[218:219]
	v_pk_add_f32 v[24:25], v[24:25], v[216:217]
	s_cbranch_vccnz .LBB0_661
	global_store_dwordx4 v[130:131], v[24:27], off offset:512
.LBB0_661:
	s_and_b64 vcc, exec, s[8:9]
	v_pk_add_f32 v[30:31], v[30:31], v[222:223]
	v_pk_add_f32 v[28:29], v[28:29], v[220:221]
	s_cbranch_vccnz .LBB0_663
	global_store_dwordx4 v[130:131], v[28:31], off offset:576
.LBB0_663:
	s_mov_b32 s100, 0x200000
	v_lshl_add_u64 v[246:247], v[240:241], 0, s[100:101]
	global_load_dwordx4 v[208:211], v[246:247], off
	global_load_dwordx4 v[212:215], v[246:247], off offset:64
	global_load_dwordx4 v[216:219], v[246:247], off offset:512
	global_load_dwordx4 v[220:223], v[246:247], off offset:576
	v_mul_f32_e32 v130, v17, v17
	v_mul_f32_e32 v131, v21, v21
	v_fmac_f32_e32 v130, v16, v16
	v_fmac_f32_e32 v131, v20, v20
	v_fmac_f32_e32 v130, v18, v18
	v_fmac_f32_e32 v131, v22, v22
	v_fmac_f32_e32 v130, v19, v19
	v_fmac_f32_e32 v131, v23, v23
	v_add_f32_e32 v130, v130, v131
	v_mul_f32_e32 v131, v25, v25
	v_fmac_f32_e32 v131, v24, v24
	v_fmac_f32_e32 v131, v26, v26
	v_fmac_f32_e32 v131, v27, v27
	v_add_f32_e32 v130, v130, v131
	v_mul_f32_e32 v131, v29, v29
	v_fmac_f32_e32 v131, v28, v28
	v_fmac_f32_e32 v131, v30, v30
	v_fmac_f32_e32 v131, v31, v31
	v_add_f32_e32 v130, v130, v131
	ds_bpermute_b32 v131, v134, v130
	s_waitcnt lgkmcnt(0)
	v_add_f32_e32 v130, v130, v131
	ds_bpermute_b32 v131, v135, v130
	s_and_saveexec_b64 s[40:41], s[0:1]
	s_cbranch_execz .LBB0_668
	s_waitcnt lgkmcnt(0)
	v_add_f32_e32 v132, v130, v131
	v_lshlrev_b64 v[130:131], 8, v[158:159]
	v_lshl_add_u64 v[130:131], s[44:45], 0, v[130:131]
	v_lshl_add_u64 v[130:131], s[2:3], 2, v[130:131]
	v_lshl_add_u64 v[130:131], v[130:131], 0, v[146:147]
	s_and_b64 vcc, exec, s[8:9]
	s_mov_b64 s[42:43], -1
	s_cbranch_vccnz .LBB0_666
	s_mov_b64 s[42:43], 0
	global_store_dword v[130:131], v132, off

; __device__ void phase4(const Params& p) {
;     ...
;     for (int ai = 0; ai < 2; ++ai)
; #pragma unroll
;       for (int m = 0; m < 4; ++m) {
;         const int row = ACC_ROW;
;         const float* x = row < 8192 ? p.x_prompt + (size_t)row * DM : p.x_sample + (size_t)(row - 8192) * DM;
;         float ss = 0.f;
; #pragma unroll
;         for (int bj = 0; bj < 2; ++bj)
; #pragma unroll
;           for (int n = 0; n < 2; ++n) {
;             const int col = ACC_COL;
;             f32x4 xv = *(const f32x4*)(x + col);
;             f32x4 v = xv + acc[ai][bj][m][n];
;             ss += v[0] * v[0] + v[1] * v[1] + v[2] * v[2] + v[3] * v[3];
;             acc[ai][bj][m][n] = v;
;             if (!fused) *(f32x4*)(p.out + (size_t)row * DM + col) = v;
;           }
;         ss += __shfl_xor(ss, 16);
;         ss += __shfl_xor(ss, 32);
;         if (fq == 0) {
;           if (fused) __hip_atomic_store(p.PART + (size_t)row * 64 + pn * 4 + wc, ss, __ATOMIC_RELAXED, __HIP_MEMORY_SCOPE_AGENT);
;           else p.PART[(size_t)row * 64 + pn * 4 + wc] = ss;
;         }
.LBB0_672:
	s_or_b64 exec, exec, s[40:41]
	v_lshl_add_u64 v[132:133], v[128:129], 2, v[132:133]
	s_waitcnt lgkmcnt(0)
	v_lshl_add_u64 v[156:157], s[22:23], 0, v[130:131]
	s_and_b64 vcc, exec, s[8:9]
	v_lshl_add_u64 v[130:131], v[128:129], 2, v[156:157]
	s_waitcnt vmcnt(10)
	v_pk_add_f32 v[34:35], v[34:35], v[226:227]
	v_pk_add_f32 v[32:33], v[32:33], v[224:225]
	s_cbranch_vccnz .LBB0_674
	global_store_dwordx4 v[130:131], v[32:35], off
.LBB0_674:
	s_and_b64 vcc, exec, s[8:9]
	v_pk_add_f32 v[38:39], v[38:39], v[230:231]
	v_pk_add_f32 v[36:37], v[36:37], v[228:229]
	s_cbranch_vccnz .LBB0_676
	global_store_dwordx4 v[130:131], v[36:39], off offset:64
.LBB0_676:
	s_and_b64 vcc, exec, s[8:9]
	v_pk_add_f32 v[42:43], v[42:43], v[234:235]
	v_pk_add_f32 v[40:41], v[40:41], v[232:233]
	s_cbranch_vccnz .LBB0_678
	global_store_dwordx4 v[130:131], v[40:43], off offset:512
.LBB0_678:
	s_and_b64 vcc, exec, s[8:9]
	v_pk_add_f32 v[46:47], v[46:47], v[238:239]
	v_pk_add_f32 v[44:45], v[44:45], v[236:237]
	s_cbranch_vccnz .LBB0_680
	global_store_dwordx4 v[130:131], v[44:47], off offset:576
.LBB0_680:
	s_mov_b32 s100, 0x240000
	v_lshl_add_u64 v[246:247], v[240:241], 0, s[100:101]
	global_load_dwordx4 v[224:227], v[246:247], off
	global_load_dwordx4 v[228:231], v[246:247], off offset:64
	global_load_dwordx4 v[232:235], v[246:247], off offset:512
	global_load_dwordx4 v[236:239], v[246:247], off offset:576
	v_mul_f32_e32 v130, v33, v33
	v_mul_f32_e32 v131, v37, v37
	v_fmac_f32_e32 v130, v32, v32
	v_fmac_f32_e32 v131, v36, v36
	v_fmac_f32_e32 v130, v34, v34
	v_fmac_f32_e32 v131, v38, v38
	v_fmac_f32_e32 v130, v35, v35
	v_fmac_f32_e32 v131, v39, v39
	v_add_f32_e32 v130, v130, v131
	v_mul_f32_e32 v131, v41, v41
	v_fmac_f32_e32 v131, v40, v40
	v_fmac_f32_e32 v131, v42, v42
	v_fmac_f32_e32 v131, v43, v43
	v_add_f32_e32 v130, v130, v131
	v_mul_f32_e32 v131, v45, v45
	v_fmac_f32_e32 v131, v44, v44
	v_fmac_f32_e32 v131, v46, v46
	v_fmac_f32_e32 v131, v47, v47
	v_add_f32_e32 v130, v130, v131
	ds_bpermute_b32 v131, v134, v130
	s_waitcnt lgkmcnt(0)
	v_add_f32_e32 v130, v130, v131
	ds_bpermute_b32 v131, v135, v130
	s_and_saveexec_b64 s[40:41], s[0:1]
	s_cbranch_execz .LBB0_685
	s_waitcnt lgkmcnt(0)
	v_add_f32_e32 v132, v130, v131
	v_lshlrev_b64 v[130:131], 8, v[162:163]
	v_lshl_add_u64 v[130:131], s[44:45], 0, v[130:131]
	v_lshl_add_u64 v[130:131], s[2:3], 2, v[130:131]
	v_lshl_add_u64 v[130:131], v[130:131], 0, v[146:147]
	s_and_b64 vcc, exec, s[8:9]
	s_mov_b64 s[42:43], -1
	s_cbranch_vccnz .LBB0_683
	s_mov_b64 s[42:43], 0
	global_store_dword v[130:131], v132, off

; __device__ void phase4(const Params& p) {
;     ...
;     for (int ai = 0; ai < 2; ++ai)
; #pragma unroll
;       for (int m = 0; m < 4; ++m) {
;         const int row = ACC_ROW;
;         const float* x = row < 8192 ? p.x_prompt + (size_t)row * DM : p.x_sample + (size_t)(row - 8192) * DM;
;         float ss = 0.f;
; #pragma unroll
;         for (int bj = 0; bj < 2; ++bj)
; #pragma unroll
;           for (int n = 0; n < 2; ++n) {
;             const int col = ACC_COL;
;             f32x4 xv = *(const f32x4*)(x + col);
;             f32x4 v = xv + acc[ai][bj][m][n];
;             ss += v[0] * v[0] + v[1] * v[1] + v[2] * v[2] + v[3] * v[3];
;             acc[ai][bj][m][n] = v;
;             if (!fused) *(f32x4*)(p.out + (size_t)row * DM + col) = v;
;           }
;         ss += __shfl_xor(ss, 16);
;         ss += __shfl_xor(ss, 32);
;         if (fq == 0) {
;           if (fused) __hip_atomic_store(p.PART + (size_t)row * 64 + pn * 4 + wc, ss, __ATOMIC_RELAXED, __HIP_MEMORY_SCOPE_AGENT);
;           else p.PART[(size_t)row * 64 + pn * 4 + wc] = ss;
;         }
.LBB0_689:
	s_or_b64 exec, exec, s[40:41]
	v_lshl_add_u64 v[132:133], v[128:129], 2, v[132:133]
	s_waitcnt lgkmcnt(0)
	v_lshl_add_u64 v[160:161], s[22:23], 0, v[130:131]
	s_and_b64 vcc, exec, s[8:9]
	v_lshl_add_u64 v[130:131], v[128:129], 2, v[160:161]
	s_waitcnt vmcnt(11)
	v_pk_add_f32 v[66:67], v[66:67], v[194:195]
	v_pk_add_f32 v[64:65], v[64:65], v[192:193]
	s_cbranch_vccnz .LBB0_691
	global_store_dwordx4 v[130:131], v[64:67], off
.LBB0_691:
	s_and_b64 vcc, exec, s[8:9]
	v_pk_add_f32 v[70:71], v[70:71], v[198:199]
	v_pk_add_f32 v[68:69], v[68:69], v[196:197]
	s_cbranch_vccnz .LBB0_693
	global_store_dwordx4 v[130:131], v[68:71], off offset:64
.LBB0_693:
	s_and_b64 vcc, exec, s[8:9]
	v_pk_add_f32 v[74:75], v[74:75], v[202:203]
	v_pk_add_f32 v[72:73], v[72:73], v[200:201]
	s_cbranch_vccnz .LBB0_695
	global_store_dwordx4 v[130:131], v[72:75], off offset:512
.LBB0_695:
	s_and_b64 vcc, exec, s[8:9]
	v_pk_add_f32 v[78:79], v[78:79], v[206:207]
	v_pk_add_f32 v[76:77], v[76:77], v[204:205]
	s_cbranch_vccnz .LBB0_697
	global_store_dwordx4 v[130:131], v[76:79], off offset:576
.LBB0_697:
	s_mov_b32 s100, 0x280000
	v_lshl_add_u64 v[246:247], v[240:241], 0, s[100:101]
	global_load_dwordx4 v[192:195], v[246:247], off
	global_load_dwordx4 v[196:199], v[246:247], off offset:64
	global_load_dwordx4 v[200:203], v[246:247], off offset:512
	global_load_dwordx4 v[204:207], v[246:247], off offset:576
	v_mul_f32_e32 v130, v65, v65
	v_mul_f32_e32 v131, v69, v69
	v_fmac_f32_e32 v130, v64, v64
	v_fmac_f32_e32 v131, v68, v68
	v_fmac_f32_e32 v130, v66, v66
	v_fmac_f32_e32 v131, v70, v70
	v_fmac_f32_e32 v130, v67, v67
	v_fmac_f32_e32 v131, v71, v71
	v_add_f32_e32 v130, v130, v131
	v_mul_f32_e32 v131, v73, v73
	v_fmac_f32_e32 v131, v72, v72
	v_fmac_f32_e32 v131, v74, v74
	v_fmac_f32_e32 v131, v75, v75
	v_add_f32_e32 v130, v130, v131
	v_mul_f32_e32 v131, v77, v77
	v_fmac_f32_e32 v131, v76, v76
	v_fmac_f32_e32 v131, v78, v78
	v_fmac_f32_e32 v131, v79, v79
	v_add_f32_e32 v130, v130, v131
	ds_bpermute_b32 v131, v134, v130
	s_waitcnt lgkmcnt(0)
	v_add_f32_e32 v130, v130, v131
	ds_bpermute_b32 v131, v135, v130
	s_and_saveexec_b64 s[40:41], s[0:1]
	s_cbranch_execz .LBB0_702
	s_waitcnt lgkmcnt(0)
	v_add_f32_e32 v132, v130, v131
	v_lshlrev_b64 v[130:131], 8, v[166:167]
	v_lshl_add_u64 v[130:131], s[44:45], 0, v[130:131]
	v_lshl_add_u64 v[130:131], s[2:3], 2, v[130:131]
	v_lshl_add_u64 v[130:131], v[130:131], 0, v[146:147]
	s_and_b64 vcc, exec, s[8:9]
	s_mov_b64 s[42:43], -1
	s_cbranch_vccnz .LBB0_700
	s_mov_b64 s[42:43], 0
	global_store_dword v[130:131], v132, off

; __device__ void phase4(const Params& p) {
;     ...
;     for (int ai = 0; ai < 2; ++ai)
; #pragma unroll
;       for (int m = 0; m < 4; ++m) {
;         const int row = ACC_ROW;
;         const float* x = row < 8192 ? p.x_prompt + (size_t)row * DM : p.x_sample + (size_t)(row - 8192) * DM;
;         float ss = 0.f;
; #pragma unroll
;         for (int bj = 0; bj < 2; ++bj)
; #pragma unroll
;           for (int n = 0; n < 2; ++n) {
;             const int col = ACC_COL;
;             f32x4 xv = *(const f32x4*)(x + col);
;             f32x4 v = xv + acc[ai][bj][m][n];
;             ss += v[0] * v[0] + v[1] * v[1] + v[2] * v[2] + v[3] * v[3];
;             acc[ai][bj][m][n] = v;
;             if (!fused) *(f32x4*)(p.out + (size_t)row * DM + col) = v;
;           }
;         ss += __shfl_xor(ss, 16);
;         ss += __shfl_xor(ss, 32);
;         if (fq == 0) {
;           if (fused) __hip_atomic_store(p.PART + (size_t)row * 64 + pn * 4 + wc, ss, __ATOMIC_RELAXED, __HIP_MEMORY_SCOPE_AGENT);
;           else p.PART[(size_t)row * 64 + pn * 4 + wc] = ss;
;         }
.LBB0_706:
	s_or_b64 exec, exec, s[40:41]
	v_lshl_add_u64 v[132:133], v[128:129], 2, v[132:133]
	s_waitcnt lgkmcnt(0)
	v_lshl_add_u64 v[164:165], s[22:23], 0, v[130:131]
	s_and_b64 vcc, exec, s[8:9]
	v_lshl_add_u64 v[130:131], v[128:129], 2, v[164:165]
	s_waitcnt vmcnt(11)
	v_pk_add_f32 v[98:99], v[98:99], v[210:211]
	v_pk_add_f32 v[96:97], v[96:97], v[208:209]
	s_cbranch_vccnz .LBB0_708
	global_store_dwordx4 v[130:131], v[96:99], off
.LBB0_708:
	s_and_b64 vcc, exec, s[8:9]
	v_pk_add_f32 v[102:103], v[102:103], v[214:215]
	v_pk_add_f32 v[100:101], v[100:101], v[212:213]
	s_cbranch_vccnz .LBB0_710
	global_store_dwordx4 v[130:131], v[100:103], off offset:64
.LBB0_710:
	s_and_b64 vcc, exec, s[8:9]
	v_pk_add_f32 v[106:107], v[106:107], v[218:219]
	v_pk_add_f32 v[104:105], v[104:105], v[216:217]
	s_cbranch_vccnz .LBB0_712
	global_store_dwordx4 v[130:131], v[104:107], off offset:512
.LBB0_712:
	s_and_b64 vcc, exec, s[8:9]
	v_pk_add_f32 v[110:111], v[110:111], v[222:223]
	v_pk_add_f32 v[108:109], v[108:109], v[220:221]
	s_cbranch_vccnz .LBB0_714
	global_store_dwordx4 v[130:131], v[108:111], off offset:576
.LBB0_714:
	s_mov_b32 s100, 0x2c0000
	v_lshl_add_u64 v[246:247], v[240:241], 0, s[100:101]
	global_load_dwordx4 v[208:211], v[246:247], off
	global_load_dwordx4 v[212:215], v[246:247], off offset:64
	global_load_dwordx4 v[216:219], v[246:247], off offset:512
	global_load_dwordx4 v[220:223], v[246:247], off offset:576
	v_mul_f32_e32 v130, v97, v97
	v_mul_f32_e32 v131, v101, v101
	v_fmac_f32_e32 v130, v96, v96
	v_fmac_f32_e32 v131, v100, v100
	v_fmac_f32_e32 v130, v98, v98
	v_fmac_f32_e32 v131, v102, v102
	v_fmac_f32_e32 v130, v99, v99
	v_fmac_f32_e32 v131, v103, v103
	v_add_f32_e32 v130, v130, v131
	v_mul_f32_e32 v131, v105, v105
	v_fmac_f32_e32 v131, v104, v104
	v_fmac_f32_e32 v131, v106, v106
	v_fmac_f32_e32 v131, v107, v107
	v_add_f32_e32 v130, v130, v131
	v_mul_f32_e32 v131, v109, v109
	v_fmac_f32_e32 v131, v108, v108
	v_fmac_f32_e32 v131, v110, v110
	v_fmac_f32_e32 v131, v111, v111
	v_add_f32_e32 v130, v130, v131
	ds_bpermute_b32 v131, v134, v130
	s_waitcnt lgkmcnt(0)
	v_add_f32_e32 v130, v130, v131
	ds_bpermute_b32 v131, v135, v130
	s_and_saveexec_b64 s[40:41], s[0:1]
	s_cbranch_execz .LBB0_719
	s_waitcnt lgkmcnt(0)
	v_add_f32_e32 v132, v130, v131
	v_lshlrev_b64 v[130:131], 8, v[170:171]
	v_lshl_add_u64 v[130:131], s[44:45], 0, v[130:131]
	v_lshl_add_u64 v[130:131], s[2:3], 2, v[130:131]
	v_lshl_add_u64 v[130:131], v[130:131], 0, v[146:147]
	s_and_b64 vcc, exec, s[8:9]
	s_mov_b64 s[42:43], -1
	s_cbranch_vccnz .LBB0_717
	s_mov_b64 s[42:43], 0
	global_store_dword v[130:131], v132, off

; __device__ void phase4(const Params& p) {
;     ...
; #pragma unroll
;         for (int bj = 0; bj < 2; ++bj)
; #pragma unroll
;           for (int n = 0; n < 2; ++n) {
;             const int col = ACC_COL;
;             f32x4 xv = *(const f32x4*)(x + col);
;             f32x4 v = xv + acc[ai][bj][m][n];
;             ss += v[0] * v[0] + v[1] * v[1] + v[2] * v[2] + v[3] * v[3];
;             acc[ai][bj][m][n] = v;
;             if (!fused) *(f32x4*)(p.out + (size_t)row * DM + col) = v;
;           }
.LBB0_723:
	s_or_b64 exec, exec, s[40:41]
	v_lshl_add_u64 v[132:133], v[128:129], 2, v[132:133]
	s_waitcnt lgkmcnt(0)
	v_lshl_add_u64 v[168:169], s[22:23], 0, v[130:131]
	s_and_b64 vcc, exec, s[8:9]
	v_lshl_add_u64 v[130:131], v[128:129], 2, v[168:169]
	s_waitcnt vmcnt(11)
	v_pk_add_f32 v[126:127], v[126:127], v[226:227]
	v_pk_add_f32 v[124:125], v[124:125], v[224:225]
	s_cbranch_vccnz .LBB0_725
	global_store_dwordx4 v[130:131], v[124:127], off
.LBB0_725:
	s_and_b64 vcc, exec, s[8:9]
	v_pk_add_f32 v[122:123], v[122:123], v[230:231]
	v_pk_add_f32 v[120:121], v[120:121], v[228:229]
	s_cbranch_vccnz .LBB0_727
	global_store_dwordx4 v[130:131], v[120:123], off offset:64
.LBB0_727:
	s_and_b64 vcc, exec, s[8:9]
	v_pk_add_f32 v[118:119], v[118:119], v[234:235]
	v_pk_add_f32 v[116:117], v[116:117], v[232:233]
	s_cbranch_vccnz .LBB0_729
	global_store_dwordx4 v[130:131], v[116:119], off offset:512
.LBB0_729:
	s_and_b64 vcc, exec, s[8:9]
	v_pk_add_f32 v[114:115], v[114:115], v[238:239]
	v_pk_add_f32 v[112:113], v[112:113], v[236:237]
	s_cbranch_vccnz .LBB0_731
	global_store_dwordx4 v[130:131], v[112:115], off offset:576

; __device__ void phase4(const Params& p) {
;     ...
; #pragma unroll
;         for (int bj = 0; bj < 2; ++bj)
; #pragma unroll
;           for (int n = 0; n < 2; ++n) {
;             const int col = ACC_COL;
;             f32x4 xv = *(const f32x4*)(x + col);
;             f32x4 v = xv + acc[ai][bj][m][n];
;             ss += v[0] * v[0] + v[1] * v[1] + v[2] * v[2] + v[3] * v[3];
;             acc[ai][bj][m][n] = v;
;             if (!fused) *(f32x4*)(p.out + (size_t)row * DM + col) = v;
;           }
.LBB0_740:
	s_or_b64 exec, exec, s[40:41]
	v_lshl_add_u64 v[132:133], v[128:129], 2, v[132:133]
	s_waitcnt lgkmcnt(0)
	v_lshl_add_u64 v[174:175], s[22:23], 0, v[130:131]
	s_and_b64 vcc, exec, s[8:9]
	v_lshl_add_u64 v[130:131], v[128:129], 2, v[174:175]
	s_waitcnt vmcnt(7)
	v_pk_add_f32 v[94:95], v[94:95], v[194:195]
	v_pk_add_f32 v[92:93], v[92:93], v[192:193]
	s_cbranch_vccnz .LBB0_742
	global_store_dwordx4 v[130:131], v[92:95], off
.LBB0_742:
	s_and_b64 vcc, exec, s[8:9]
	v_pk_add_f32 v[90:91], v[90:91], v[198:199]
	v_pk_add_f32 v[88:89], v[88:89], v[196:197]
	s_cbranch_vccnz .LBB0_744
	global_store_dwordx4 v[130:131], v[88:91], off offset:64
.LBB0_744:
	s_and_b64 vcc, exec, s[8:9]
	v_pk_add_f32 v[86:87], v[86:87], v[202:203]
	v_pk_add_f32 v[84:85], v[84:85], v[200:201]
	s_cbranch_vccnz .LBB0_746
	global_store_dwordx4 v[130:131], v[84:87], off offset:512
.LBB0_746:
	s_and_b64 vcc, exec, s[8:9]
	v_pk_add_f32 v[82:83], v[82:83], v[206:207]
	v_pk_add_f32 v[80:81], v[80:81], v[204:205]
	s_cbranch_vccnz .LBB0_748
	global_store_dwordx4 v[130:131], v[80:83], off offset:576

; __device__ void phase4(const Params& p) {
;     ...
; #pragma unroll
;         for (int bj = 0; bj < 2; ++bj)
; #pragma unroll
;           for (int n = 0; n < 2; ++n) {
;             const int col = ACC_COL;
;             f32x4 xv = *(const f32x4*)(x + col);
;             f32x4 v = xv + acc[ai][bj][m][n];
;             ss += v[0] * v[0] + v[1] * v[1] + v[2] * v[2] + v[3] * v[3];
;             acc[ai][bj][m][n] = v;
;             if (!fused) *(f32x4*)(p.out + (size_t)row * DM + col) = v;
;           }
.LBB0_757:
	s_or_b64 exec, exec, s[40:41]
	v_lshl_add_u64 v[132:133], v[128:129], 2, v[132:133]
	s_waitcnt lgkmcnt(0)
	v_lshl_add_u64 v[178:179], s[22:23], 0, v[130:131]
	s_and_b64 vcc, exec, s[8:9]
	v_lshl_add_u64 v[130:131], v[128:129], 2, v[178:179]
	s_waitcnt vmcnt(3)
	v_pk_add_f32 v[62:63], v[62:63], v[210:211]
	v_pk_add_f32 v[60:61], v[60:61], v[208:209]
	s_cbranch_vccnz .LBB0_759
	global_store_dwordx4 v[130:131], v[60:63], off
.LBB0_759:
	s_and_b64 vcc, exec, s[8:9]
	v_pk_add_f32 v[58:59], v[58:59], v[214:215]
	v_pk_add_f32 v[56:57], v[56:57], v[212:213]
	s_cbranch_vccnz .LBB0_761
	global_store_dwordx4 v[130:131], v[56:59], off offset:64
.LBB0_761:
	s_and_b64 vcc, exec, s[8:9]
	v_pk_add_f32 v[54:55], v[54:55], v[218:219]
	v_pk_add_f32 v[52:53], v[52:53], v[216:217]
	s_cbranch_vccnz .LBB0_763
	global_store_dwordx4 v[130:131], v[52:55], off offset:512
.LBB0_763:
	s_and_b64 vcc, exec, s[8:9]
	v_pk_add_f32 v[50:51], v[50:51], v[222:223]
	v_pk_add_f32 v[48:49], v[48:49], v[220:221]
	s_cbranch_vccnz .LBB0_765
	global_store_dwordx4 v[130:131], v[48:51], off offset:576
